# attention row sums by v_pk_add_f32 into two partial sums (16 packed adds per tile instead of 32 scalar adds)
# baseline (speedup 1.0000x reference)
.LBB0_1480:
	v_readfirstlane_b32 s44, v203
	v_readfirstlane_b32 s45, v205
	s_mov_b64 s[40:41], s[94:95]
	s_mov_b64 s[42:43], s[94:95]
	s_movk_i32 s46, 0x41
	s_add_u32 s45, s45, 0x2000
	v_mov_b32_e32 v183, v188
	v_mul_f32_e32 v189, 0.5, v189
	v_mov_b32_e32 v188, 0

.Latt_cont_a:
	v_exp_f32_e32 v112, v112
	v_exp_f32_e32 v113, v113
	v_exp_f32_e32 v114, v114
	v_exp_f32_e32 v115, v115
	v_exp_f32_e32 v116, v116
	v_exp_f32_e32 v117, v117
	v_exp_f32_e32 v118, v118
	v_exp_f32_e32 v119, v119
	v_pk_add_f32 v[188:189], v[188:189], v[112:113]
	v_pk_add_f32 v[188:189], v[188:189], v[114:115]
	v_pk_add_f32 v[188:189], v[188:189], v[116:117]
	v_pk_add_f32 v[188:189], v[188:189], v[118:119]
	v_cvt_pk_bf16_f32 v112, v112, v113
	v_cvt_pk_bf16_f32 v113, v114, v115
	v_cvt_pk_bf16_f32 v114, v116, v117
	v_cvt_pk_bf16_f32 v115, v118, v119
	v_exp_f32_e32 v120, v120
	v_exp_f32_e32 v121, v121
	s_waitcnt lgkmcnt(8)
	v_mfma_f32_32x32x16_bf16 v[48:63], v[232:235], v[112:115], v[48:63]
	v_exp_f32_e32 v122, v122
	v_exp_f32_e32 v123, v123
	v_exp_f32_e32 v124, v124
	v_mfma_f32_32x32x16_bf16 v[32:47], v[236:239], v[112:115], v[32:47]
	v_exp_f32_e32 v125, v125
	v_exp_f32_e32 v126, v126
	v_exp_f32_e32 v127, v127
	v_mfma_f32_32x32x16_bf16 v[16:31], v[240:243], v[112:115], v[16:31]
	v_pk_add_f32 v[188:189], v[188:189], v[120:121]
	v_pk_add_f32 v[188:189], v[188:189], v[122:123]
	v_pk_add_f32 v[188:189], v[188:189], v[124:125]
	v_pk_add_f32 v[188:189], v[188:189], v[126:127]
	v_cvt_pk_bf16_f32 v116, v120, v121
	v_cvt_pk_bf16_f32 v117, v122, v123
	v_mfma_f32_32x32x16_bf16 v[0:15], v[244:247], v[112:115], v[0:15]
	ds_read_b128 v[232:235], v167 offset:32768
	ds_read_b128 v[236:239], v167 offset:36864
	ds_read_b128 v[240:243], v167 offset:40960
	ds_read_b128 v[244:247], v167 offset:45056
	v_cvt_pk_bf16_f32 v118, v124, v125
	v_cvt_pk_bf16_f32 v119, v126, v127
	s_nop 0
	s_waitcnt lgkmcnt(8)
	v_mfma_f32_32x32x16_bf16 v[48:63], v[64:67], v[116:119], v[48:63]
	v_exp_f32_e32 v80, v80
	v_exp_f32_e32 v81, v81
	v_exp_f32_e32 v82, v82
	v_mfma_f32_32x32x16_bf16 v[32:47], v[68:71], v[116:119], v[32:47]
	v_exp_f32_e32 v83, v83
	v_exp_f32_e32 v84, v84
	v_exp_f32_e32 v85, v85
	v_mfma_f32_32x32x16_bf16 v[16:31], v[72:75], v[116:119], v[16:31]
	v_exp_f32_e32 v86, v86
	v_exp_f32_e32 v87, v87
	v_pk_add_f32 v[188:189], v[188:189], v[80:81]
	v_pk_add_f32 v[188:189], v[188:189], v[82:83]
	v_mfma_f32_32x32x16_bf16 v[0:15], v[76:79], v[116:119], v[0:15]
	v_pk_add_f32 v[188:189], v[188:189], v[84:85]
	v_pk_add_f32 v[188:189], v[188:189], v[86:87]
	v_cvt_pk_bf16_f32 v80, v80, v81
	v_cvt_pk_bf16_f32 v81, v82, v83
	v_cvt_pk_bf16_f32 v82, v84, v85
	v_cvt_pk_bf16_f32 v83, v86, v87
	s_nop 0
	s_waitcnt lgkmcnt(4)
	v_mfma_f32_32x32x16_bf16 v[48:63], v[216:219], v[80:83], v[48:63]
	v_exp_f32_e32 v88, v88
	v_exp_f32_e32 v89, v89
	v_exp_f32_e32 v90, v90
	v_mfma_f32_32x32x16_bf16 v[32:47], v[220:223], v[80:83], v[32:47]
	v_exp_f32_e32 v91, v91
	v_exp_f32_e32 v92, v92
	v_exp_f32_e32 v93, v93
	v_mfma_f32_32x32x16_bf16 v[16:31], v[224:227], v[80:83], v[16:31]
	v_exp_f32_e32 v94, v94
	v_exp_f32_e32 v95, v95
	v_pk_add_f32 v[188:189], v[188:189], v[88:89]
	v_pk_add_f32 v[188:189], v[188:189], v[90:91]
	v_mfma_f32_32x32x16_bf16 v[0:15], v[228:231], v[80:83], v[0:15]
	v_pk_add_f32 v[188:189], v[188:189], v[92:93]
	v_pk_add_f32 v[188:189], v[188:189], v[94:95]
	v_cvt_pk_bf16_f32 v84, v88, v89
	v_cvt_pk_bf16_f32 v85, v90, v91
	v_cvt_pk_bf16_f32 v86, v92, v93
	v_cvt_pk_bf16_f32 v87, v94, v95
	s_nop 0
	s_waitcnt lgkmcnt(0)
	v_mfma_f32_32x32x16_bf16 v[48:63], v[232:235], v[84:87], v[48:63]
	v_mfma_f32_32x32x16_bf16 v[32:47], v[236:239], v[84:87], v[32:47]
	v_mfma_f32_32x32x16_bf16 v[16:31], v[240:243], v[84:87], v[16:31]
	v_mfma_f32_32x32x16_bf16 v[0:15], v[244:247], v[84:87], v[0:15]
	s_waitcnt vmcnt(0)
	s_barrier
	ds_read_b128 v[64:67], v173 offset:0
	ds_read_b128 v[68:71], v173 offset:4096
	s_add_u32 m0, s44, 0x6000
	ds_read_b128 v[72:75], v171 offset:0
	global_load_lds_dwordx4 v200, s[40:41]
	s_add_u32 m0, s44, 0x6400
	ds_read_b128 v[76:79], v171 offset:4096
	global_load_lds_dwordx4 v190, s[40:41]
	s_add_u32 m0, s45, 0x6000
	ds_read_b128 v[216:219], v169 offset:0
	global_load_lds_dwordx4 v192, s[42:43]
	s_add_u32 m0, s45, 0x6400
	ds_read_b128 v[220:223], v169 offset:4096
	global_load_lds_dwordx4 v194, s[42:43]
	s_add_u32 m0, s45, 0x6800
	ds_read_b128 v[224:227], v167 offset:0
	global_load_lds_dwordx4 v196, s[42:43]
	s_add_u32 m0, s45, 0x6c00
	ds_read_b128 v[228:231], v167 offset:4096
	global_load_lds_dwordx4 v198, s[42:43]
	ds_read_b128 v[232:235], v173 offset:8192
	ds_read_b128 v[236:239], v173 offset:12288
	ds_read_b128 v[240:243], v173 offset:16384
	ds_read_b128 v[244:247], v173 offset:20480
	s_add_u32 s40, s40, 0x18000
	s_addc_u32 s41, s41, 0
	s_add_u32 s42, s42, 0x80
	s_addc_u32 s43, s43, 0
	s_waitcnt lgkmcnt(11)
	v_mfma_f32_32x32x16_bf16 v[112:127], v[64:67], v[140:143], v[96:111]
	ds_read_b128 v[64:67], v171 offset:8192
	s_waitcnt lgkmcnt(11)
	v_mfma_f32_32x32x16_bf16 v[80:95], v[68:71], v[140:143], v[96:111]
	ds_read_b128 v[68:71], v171 offset:12288
	s_waitcnt lgkmcnt(11)
	v_mfma_f32_32x32x16_bf16 v[112:127], v[72:75], v[136:139], v[112:127]
	ds_read_b128 v[72:75], v171 offset:16384
	s_waitcnt lgkmcnt(11)
	v_mfma_f32_32x32x16_bf16 v[80:95], v[76:79], v[136:139], v[80:95]
	ds_read_b128 v[76:79], v171 offset:20480
	s_waitcnt lgkmcnt(11)
	v_mfma_f32_32x32x16_bf16 v[112:127], v[216:219], v[132:135], v[112:127]
	ds_read_b128 v[216:219], v169 offset:8192
	s_waitcnt lgkmcnt(11)
	v_mfma_f32_32x32x16_bf16 v[80:95], v[220:223], v[132:135], v[80:95]
	ds_read_b128 v[220:223], v169 offset:12288
	s_waitcnt lgkmcnt(11)
	v_mfma_f32_32x32x16_bf16 v[112:127], v[224:227], v[128:131], v[112:127]
	ds_read_b128 v[224:227], v169 offset:16384
	s_waitcnt lgkmcnt(11)
	v_mfma_f32_32x32x16_bf16 v[80:95], v[228:231], v[128:131], v[80:95]
	ds_read_b128 v[228:231], v169 offset:20480
	s_nop 7
	s_nop 3
	v_max3_f32 v175, v112, v113, v114
	v_max3_f32 v177, v115, v116, v117
	v_max3_f32 v179, v118, v119, v120
	v_max3_f32 v181, v121, v122, v123
	v_max3_f32 v248, v124, v125, v126
	v_max3_f32 v249, v127, v80, v81
	v_max3_f32 v250, v82, v83, v84
	v_max3_f32 v251, v85, v86, v87
	v_max3_f32 v253, v88, v89, v90
	v_max3_f32 v254, v91, v92, v93
	v_max3_f32 v175, v175, v177, v179
	v_max3_f32 v181, v181, v248, v249
	v_max3_f32 v250, v250, v251, v253
	v_max3_f32 v254, v254, v94, v95
	v_max3_f32 v175, v175, v181, v250
	v_max_f32_e32 v175, v175, v254
	v_cmp_lt_f32_e32 vcc, 0x41000000, v175
	s_cbranch_vccnz .Latt_resc_b
.Latt_cont_b:
	v_exp_f32_e32 v112, v112
	v_exp_f32_e32 v113, v113
	v_exp_f32_e32 v114, v114
	v_exp_f32_e32 v115, v115
	v_exp_f32_e32 v116, v116
	v_exp_f32_e32 v117, v117
	v_exp_f32_e32 v118, v118
	v_exp_f32_e32 v119, v119
	v_pk_add_f32 v[188:189], v[188:189], v[112:113]
	v_pk_add_f32 v[188:189], v[188:189], v[114:115]
	v_pk_add_f32 v[188:189], v[188:189], v[116:117]
	v_pk_add_f32 v[188:189], v[188:189], v[118:119]
	v_cvt_pk_bf16_f32 v112, v112, v113
	v_cvt_pk_bf16_f32 v113, v114, v115
	v_cvt_pk_bf16_f32 v114, v116, v117
	v_cvt_pk_bf16_f32 v115, v118, v119
	v_exp_f32_e32 v120, v120
	v_exp_f32_e32 v121, v121
	s_waitcnt lgkmcnt(8)
	v_mfma_f32_32x32x16_bf16 v[48:63], v[232:235], v[112:115], v[48:63]
	v_exp_f32_e32 v122, v122
	v_exp_f32_e32 v123, v123
	v_exp_f32_e32 v124, v124
	v_mfma_f32_32x32x16_bf16 v[32:47], v[236:239], v[112:115], v[32:47]
	v_exp_f32_e32 v125, v125
	v_exp_f32_e32 v126, v126
	v_exp_f32_e32 v127, v127
	v_mfma_f32_32x32x16_bf16 v[16:31], v[240:243], v[112:115], v[16:31]
	v_pk_add_f32 v[188:189], v[188:189], v[120:121]
	v_pk_add_f32 v[188:189], v[188:189], v[122:123]
	v_pk_add_f32 v[188:189], v[188:189], v[124:125]
	v_pk_add_f32 v[188:189], v[188:189], v[126:127]
	v_cvt_pk_bf16_f32 v116, v120, v121
	v_cvt_pk_bf16_f32 v117, v122, v123
	v_mfma_f32_32x32x16_bf16 v[0:15], v[244:247], v[112:115], v[0:15]
	ds_read_b128 v[232:235], v167 offset:8192
	ds_read_b128 v[236:239], v167 offset:12288
	ds_read_b128 v[240:243], v167 offset:16384
	ds_read_b128 v[244:247], v167 offset:20480
	v_cvt_pk_bf16_f32 v118, v124, v125
	v_cvt_pk_bf16_f32 v119, v126, v127
	s_nop 0
	s_waitcnt lgkmcnt(8)
	v_mfma_f32_32x32x16_bf16 v[48:63], v[64:67], v[116:119], v[48:63]
	v_exp_f32_e32 v80, v80
	v_exp_f32_e32 v81, v81
	v_exp_f32_e32 v82, v82
	v_mfma_f32_32x32x16_bf16 v[32:47], v[68:71], v[116:119], v[32:47]
	v_exp_f32_e32 v83, v83
	v_exp_f32_e32 v84, v84
	v_exp_f32_e32 v85, v85
	v_mfma_f32_32x32x16_bf16 v[16:31], v[72:75], v[116:119], v[16:31]
	v_exp_f32_e32 v86, v86
	v_exp_f32_e32 v87, v87
	v_pk_add_f32 v[188:189], v[188:189], v[80:81]
	v_pk_add_f32 v[188:189], v[188:189], v[82:83]
	v_mfma_f32_32x32x16_bf16 v[0:15], v[76:79], v[116:119], v[0:15]
	v_pk_add_f32 v[188:189], v[188:189], v[84:85]
	v_pk_add_f32 v[188:189], v[188:189], v[86:87]
	v_cvt_pk_bf16_f32 v80, v80, v81
	v_cvt_pk_bf16_f32 v81, v82, v83
	v_cvt_pk_bf16_f32 v82, v84, v85
	v_cvt_pk_bf16_f32 v83, v86, v87
	s_nop 0
	s_waitcnt lgkmcnt(4)
	v_mfma_f32_32x32x16_bf16 v[48:63], v[216:219], v[80:83], v[48:63]
	v_exp_f32_e32 v88, v88
	v_exp_f32_e32 v89, v89
	v_exp_f32_e32 v90, v90
	v_mfma_f32_32x32x16_bf16 v[32:47], v[220:223], v[80:83], v[32:47]
	v_exp_f32_e32 v91, v91
	v_exp_f32_e32 v92, v92
	v_exp_f32_e32 v93, v93
	v_mfma_f32_32x32x16_bf16 v[16:31], v[224:227], v[80:83], v[16:31]
	v_exp_f32_e32 v94, v94
	v_exp_f32_e32 v95, v95
	v_pk_add_f32 v[188:189], v[188:189], v[88:89]
	v_pk_add_f32 v[188:189], v[188:189], v[90:91]
	v_mfma_f32_32x32x16_bf16 v[0:15], v[228:231], v[80:83], v[0:15]
	v_pk_add_f32 v[188:189], v[188:189], v[92:93]
	v_pk_add_f32 v[188:189], v[188:189], v[94:95]
	v_cvt_pk_bf16_f32 v84, v88, v89
	v_cvt_pk_bf16_f32 v85, v90, v91
	v_cvt_pk_bf16_f32 v86, v92, v93
	v_cvt_pk_bf16_f32 v87, v94, v95
	s_nop 0
	s_waitcnt lgkmcnt(0)
	v_mfma_f32_32x32x16_bf16 v[48:63], v[232:235], v[84:87], v[48:63]
	v_mfma_f32_32x32x16_bf16 v[32:47], v[236:239], v[84:87], v[32:47]
	v_mfma_f32_32x32x16_bf16 v[16:31], v[240:243], v[84:87], v[16:31]
	v_mfma_f32_32x32x16_bf16 v[0:15], v[244:247], v[84:87], v[0:15]
	s_sub_u32 s46, s46, 1
	s_cmp_lg_u32 s46, 0
	s_cbranch_scc1 .Latt_loop
	v_mov_b64_e32 v[64:65], v[96:97]
	v_mov_b64_e32 v[66:67], v[98:99]
	v_mov_b64_e32 v[68:69], v[100:101]
	v_mov_b64_e32 v[70:71], v[102:103]
	v_mov_b64_e32 v[72:73], v[104:105]
	v_mov_b64_e32 v[74:75], v[106:107]
	v_mov_b64_e32 v[76:77], v[108:109]
	v_mov_b64_e32 v[78:79], v[110:111]
	v_add_f32_e32 v189, v189, v188
	v_mov_b32_e32 v188, v183
	v_mov_b32_e32 v248, v189
	s_nop 1
	v_permlane32_swap_b32_e32 v189, v248
	v_add_f32_e32 v189, v189, v248
	s_branch .LBB0_1482
.Latt_resc_a:
	v_mov_b32_e32 v177, v175
	s_nop 1
	v_permlane32_swap_b32_e32 v175, v177
	v_max_f32_e32 v175, v175, v177
	v_max_f32_e32 v248, 0, v175
	v_exp_f32_e64 v250, -v248
	v_sub_f32_e32 v112, v112, v248
	v_sub_f32_e32 v113, v113, v248
	v_sub_f32_e32 v114, v114, v248
	v_sub_f32_e32 v115, v115, v248
	v_sub_f32_e32 v116, v116, v248
	v_sub_f32_e32 v117, v117, v248
	v_sub_f32_e32 v118, v118, v248
	v_sub_f32_e32 v119, v119, v248
	v_sub_f32_e32 v120, v120, v248
	v_sub_f32_e32 v121, v121, v248
	v_sub_f32_e32 v122, v122, v248
	v_sub_f32_e32 v123, v123, v248
	v_sub_f32_e32 v124, v124, v248
	v_sub_f32_e32 v125, v125, v248
	v_sub_f32_e32 v126, v126, v248
	v_sub_f32_e32 v127, v127, v248
	v_sub_f32_e32 v80, v80, v248
	v_sub_f32_e32 v81, v81, v248
	v_sub_f32_e32 v82, v82, v248
	v_sub_f32_e32 v83, v83, v248
	v_sub_f32_e32 v84, v84, v248
	v_sub_f32_e32 v85, v85, v248
	v_sub_f32_e32 v86, v86, v248
	v_sub_f32_e32 v87, v87, v248
	v_sub_f32_e32 v88, v88, v248
	v_sub_f32_e32 v89, v89, v248
	v_sub_f32_e32 v90, v90, v248
	v_sub_f32_e32 v91, v91, v248
	v_sub_f32_e32 v92, v92, v248
	v_sub_f32_e32 v93, v93, v248
	v_sub_f32_e32 v94, v94, v248
	v_sub_f32_e32 v95, v95, v248
	v_add_f32_e32 v183, v183, v248
	v_mul_f32_e32 v189, v189, v250
	v_mul_f32_e32 v188, v188, v250
	v_pk_mul_f32 v[0:1], v[0:1], v[250:251] op_sel_hi:[1,0]
	v_pk_mul_f32 v[2:3], v[2:3], v[250:251] op_sel_hi:[1,0]
	v_pk_mul_f32 v[4:5], v[4:5], v[250:251] op_sel_hi:[1,0]
	v_pk_mul_f32 v[6:7], v[6:7], v[250:251] op_sel_hi:[1,0]
	v_pk_mul_f32 v[8:9], v[8:9], v[250:251] op_sel_hi:[1,0]
	v_pk_mul_f32 v[10:11], v[10:11], v[250:251] op_sel_hi:[1,0]
	v_pk_mul_f32 v[12:13], v[12:13], v[250:251] op_sel_hi:[1,0]
	v_pk_mul_f32 v[14:15], v[14:15], v[250:251] op_sel_hi:[1,0]
	v_pk_mul_f32 v[16:17], v[16:17], v[250:251] op_sel_hi:[1,0]
	v_pk_mul_f32 v[18:19], v[18:19], v[250:251] op_sel_hi:[1,0]
	v_pk_mul_f32 v[20:21], v[20:21], v[250:251] op_sel_hi:[1,0]
	v_pk_mul_f32 v[22:23], v[22:23], v[250:251] op_sel_hi:[1,0]
	v_pk_mul_f32 v[24:25], v[24:25], v[250:251] op_sel_hi:[1,0]
	v_pk_mul_f32 v[26:27], v[26:27], v[250:251] op_sel_hi:[1,0]
	v_pk_mul_f32 v[28:29], v[28:29], v[250:251] op_sel_hi:[1,0]
	v_pk_mul_f32 v[30:31], v[30:31], v[250:251] op_sel_hi:[1,0]
	v_pk_mul_f32 v[32:33], v[32:33], v[250:251] op_sel_hi:[1,0]
	v_pk_mul_f32 v[34:35], v[34:35], v[250:251] op_sel_hi:[1,0]
	v_pk_mul_f32 v[36:37], v[36:37], v[250:251] op_sel_hi:[1,0]
	v_pk_mul_f32 v[38:39], v[38:39], v[250:251] op_sel_hi:[1,0]
	v_pk_mul_f32 v[40:41], v[40:41], v[250:251] op_sel_hi:[1,0]
	v_pk_mul_f32 v[42:43], v[42:43], v[250:251] op_sel_hi:[1,0]
	v_pk_mul_f32 v[44:45], v[44:45], v[250:251] op_sel_hi:[1,0]
	v_pk_mul_f32 v[46:47], v[46:47], v[250:251] op_sel_hi:[1,0]
	v_pk_mul_f32 v[48:49], v[48:49], v[250:251] op_sel_hi:[1,0]
	v_pk_mul_f32 v[50:51], v[50:51], v[250:251] op_sel_hi:[1,0]
	v_pk_mul_f32 v[52:53], v[52:53], v[250:251] op_sel_hi:[1,0]
	v_pk_mul_f32 v[54:55], v[54:55], v[250:251] op_sel_hi:[1,0]
	v_pk_mul_f32 v[56:57], v[56:57], v[250:251] op_sel_hi:[1,0]
	v_pk_mul_f32 v[58:59], v[58:59], v[250:251] op_sel_hi:[1,0]
	v_pk_mul_f32 v[60:61], v[60:61], v[250:251] op_sel_hi:[1,0]
	v_pk_mul_f32 v[62:63], v[62:63], v[250:251] op_sel_hi:[1,0]
	v_sub_f32_e32 v96, 0, v183
	v_mov_b32_e32 v97, v96
	v_mov_b32_e32 v98, v96
	v_mov_b32_e32 v99, v96
	v_mov_b32_e32 v100, v96
	v_mov_b32_e32 v101, v96
	v_mov_b32_e32 v102, v96
	v_mov_b32_e32 v103, v96
	v_mov_b32_e32 v104, v96
	v_mov_b32_e32 v105, v96
	v_mov_b32_e32 v106, v96
	v_mov_b32_e32 v107, v96
	v_mov_b32_e32 v108, v96
	v_mov_b32_e32 v109, v96
	v_mov_b32_e32 v110, v96
	v_mov_b32_e32 v111, v96
	s_branch .Latt_cont_a
